# layer-1 w_out/w_ff2 f32->bf16 tile conversion moved from phase 0 into the idle tail of layer-0 out-proj (WGs 16..255)
# baseline (speedup 1.0000x reference)
.LBB0_15:
	s_or_b64 exec, exec, s[4:5]
	s_cmpk_gt_i32 s31, 0x15bf
	s_barrier
	s_cbranch_scc1 .LBB0_114
	v_and_b32_e32 v1, 0x7f, v2
	v_ashrrev_i32_e32 v15, 7, v2
	s_movk_i32 s4, 0x204
	v_lshlrev_b32_e32 v3, 2, v1
	v_mul_lo_u32 v4, v15, s4
	v_add3_u32 v19, 0, v3, v4
	v_lshlrev_b32_e32 v3, 5, v2
	v_and_b32_e32 v4, 0x60, v3
	v_and_b32_e32 v3, -4, v2
	v_mul_u32_u24_e32 v5, 0x204, v4
	v_add3_u32 v27, 0, v3, v5
	v_and_b32_e32 v3, 3, v2
	v_lshlrev_b32_e32 v5, 3, v2
	v_and_or_b32 v28, v5, 32, v3
	v_ashrrev_i32_e32 v3, 3, v2
	v_and_b32_e32 v5, 28, v12
	s_movk_i32 s5, 0x180
	v_mul_lo_u32 v7, v3, s5
	s_add_i32 s6, 0, 0x16400
	v_lshlrev_b32_e32 v5, 2, v5
	v_ashrrev_i32_e32 v18, 5, v2
	s_movk_i32 s4, 0x60
	v_lshlrev_b32_e32 v6, 5, v3
	v_add3_u32 v29, s6, v7, v5
	v_lshlrev_b32_e32 v5, 2, v14
	v_lshlrev_b32_e32 v7, 7, v18
	s_mov_b32 s33, 0xc000
	v_ashrrev_i32_e32 v26, 2, v2
	v_cmp_gt_i32_e64 s[4:5], s4, v2
	v_add3_u32 v30, s6, v5, v7
	v_mad_i64_i32 v[6:7], s[34:35], v6, s33, 0
	v_and_b32_e32 v2, 7, v2
	v_lshl_or_b32 v6, v2, 4, v6
	s_add_u32 s6, s20, 0x34400000
	v_lshl_add_u32 v31, v3, 7, 0
	v_lshl_add_u64 v[2:3], s[22:23], 0, v[6:7]
	s_mov_b64 s[22:23], 0x54000
	v_mov_b32_e32 v17, 0
	s_addc_u32 s7, s21, 0
	v_lshl_add_u64 v[20:21], v[2:3], 0, s[22:23]
	s_mov_b32 s50, 0x8000
	s_mov_b32 s51, 0x10000
	s_mov_b32 s52, 0x18000
	s_mov_b32 s53, 0x20000
	s_mov_b32 s54, 0x28000
	s_mov_b32 s55, 0x30000
	s_mov_b32 s56, 0x38000
	s_mov_b32 s57, 0x40000
	s_mov_b32 s58, 0x48000
	s_mov_b32 s59, 0x50000
	s_mov_b32 s60, 0x58000
	s_mov_b32 s61, 0x60000
	s_mov_b32 s62, 0x68000
	s_mov_b32 s63, 0x70000
	s_mov_b32 s64, 0x78000
	s_mov_b32 s65, 0x80000
	s_mov_b32 s66, 0x88000
	s_mov_b32 s67, 0x90000
	s_mov_b32 s68, 0x98000
	s_mov_b32 s69, 0xa0000
	s_mov_b32 s70, 0xa8000
	s_mov_b32 s71, 0xb0000
	s_mov_b32 s72, 0xb8000
	s_mov_b32 s73, 0xc0000
	s_mov_b32 s74, 0xc8000
	s_mov_b32 s75, 0xd0000
	s_mov_b32 s76, 0xd8000
	s_mov_b32 s77, 0xe0000
	s_mov_b32 s78, 0xe8000
	s_mov_b32 s79, 0xf0000
	s_mov_b32 s80, 0xf8000
	s_movk_i32 s81, 0xbff
	s_movk_i32 s82, 0x1220
	s_movk_i32 s83, 0xf400
	s_movk_i32 s84, 0xc20
	s_movk_i32 s85, 0x1ff
	s_movk_i32 s86, 0x4880
	s_mov_b32 s87, 0xfffac000
	s_mov_b32 s88, 0xfffb8000
	s_mov_b32 s89, 0xfffc4000
	s_mov_b32 s90, 0xfffd0000
	s_mov_b32 s91, 0xfffdc000
	v_lshlrev_b32_e32 v22, 1, v4
	v_add_u32_e32 v32, 0x400, v27
	v_add_u32_e32 v33, 0x800, v27
	v_add_u32_e32 v34, 0xc00, v27
	v_add_u32_e32 v35, 0x1000, v27
	v_add_u32_e32 v36, 0x1400, v27
	v_add_u32_e32 v37, 0x1800, v27
	v_add_u32_e32 v38, 0x1c00, v27
	v_add_u32_e32 v39, 0x2000, v27
	v_add_u32_e32 v40, 0x2400, v27
	v_add_u32_e32 v41, 0x2800, v27
	v_add_u32_e32 v42, 0x2c00, v27
	v_add_u32_e32 v43, 0x3000, v27
	v_add_u32_e32 v44, 0x3400, v27
	v_add_u32_e32 v45, 0x3800, v27
	v_add_u32_e32 v46, 0x3c00, v27
	v_mov_b32_e32 v47, 0x3e0293ee
	v_mov_b32_e32 v48, 0x3e000000
	s_mov_b32 s92, 0xfffe8000
	s_mov_b32 s93, 0xffff4000
	s_mov_b32 s23, 0
	s_mov_b64 s[34:35], 0x3b00000
	s_mov_b64 s[36:37], 0x1b00000
	s_mov_b64 s[38:39], 0x1300000
	s_mov_b64 s[40:41], 0x60000
	s_branch .LBB0_19

.LBB0_18:
	s_add_i32 s31, s31, s28
	s_cmpk_lt_i32 s31, 0x15c0
	s_cbranch_scc0 .LBB0_114
.LBB0_19:
	s_add_i32 s22, s31, 0xffffef40
	s_cmpk_lt_u32 s22, 0x100
	s_cbranch_scc1 .LBB0_18
	s_cmpk_gt_i32 s31, 0x2ff
	s_mov_b64 s[42:43], -1
	s_cbranch_scc0 .LBB0_109
	s_add_i32 s22, s31, 0xfffffd00
	s_cmpk_gt_u32 s22, 0xb5f
	s_cselect_b64 s[44:45], -1, 0
	s_and_b64 s[42:43], s[44:45], exec
	s_cselect_b32 s94, 0xfffff4a0, 0
	s_add_i32 s94, s94, s22
	s_and_b64 s[42:43], s[44:45], exec
	s_cselect_b32 s22, 0x5b00000, 0
	s_add_u32 s42, s20, s22
	s_addc_u32 s43, s21, 0
	s_cmpk_gt_i32 s94, 0x25f
	s_mov_b64 s[46:47], -1
	s_cbranch_scc0 .LBB0_30
	s_cmpk_gt_u32 s94, 0x35f
	s_cbranch_scc0 .LBB0_27
	s_cmpk_gt_u32 s94, 0x75f
	s_cbranch_scc0 .LBB0_24
	s_add_i32 s22, s94, 0xfffff8a0
	s_and_b64 s[46:47], s[44:45], exec
	s_cselect_b32 s46, 0x4000000, 0
	s_add_u32 s48, s26, s46
	s_addc_u32 s49, s27, 0
	s_lshl_b32 s46, s22, 1
	s_lshl_b32 s22, s22, 7
	s_and_b32 s22, s22, 0x1f80
	s_and_b32 s46, s46, 0x7fffff80
	v_add_u32_e32 v2, s22, v15
	v_or_b32_e32 v16, s46, v1
	v_ashrrev_i32_e32 v3, 31, v2
	v_lshl_add_u64 v[4:5], v[16:17], 2, s[48:49]
	v_lshlrev_b64 v[2:3], 13, v[2:3]
	v_lshl_add_u64 v[2:3], v[4:5], 0, v[2:3]
	v_add_co_u32_e32 v4, vcc, s50, v2
	s_lshl_b32 s22, s22, 1
	s_nop 0
	v_addc_co_u32_e32 v5, vcc, 0, v3, vcc
	v_add_co_u32_e32 v6, vcc, s51, v2
	s_nop 1
	v_addc_co_u32_e32 v7, vcc, 0, v3, vcc
	v_add_co_u32_e32 v8, vcc, s52, v2
	s_nop 1
	v_addc_co_u32_e32 v9, vcc, 0, v3, vcc
	v_add_co_u32_e32 v10, vcc, s53, v2
	s_nop 1
	v_addc_co_u32_e32 v11, vcc, 0, v3, vcc
	v_add_co_u32_e32 v12, vcc, s54, v2
	s_nop 1
	v_addc_co_u32_e32 v13, vcc, 0, v3, vcc
	v_add_co_u32_e32 v24, vcc, s55, v2
	s_nop 1
	v_addc_co_u32_e32 v25, vcc, 0, v3, vcc
	v_add_co_u32_e32 v50, vcc, s56, v2
	s_nop 1
	v_addc_co_u32_e32 v51, vcc, 0, v3, vcc
	global_load_dword v16, v[2:3], off
	global_load_dword v23, v[4:5], off
	global_load_dword v49, v[6:7], off
	global_load_dword v54, v[8:9], off
	global_load_dword v55, v[10:11], off
	global_load_dword v56, v[12:13], off
	global_load_dword v57, v[24:25], off
	global_load_dword v58, v[50:51], off
	v_add_co_u32_e32 v4, vcc, s57, v2
	s_nop 1
	v_addc_co_u32_e32 v5, vcc, 0, v3, vcc
	v_add_co_u32_e32 v6, vcc, s58, v2
	s_nop 1
	v_addc_co_u32_e32 v7, vcc, 0, v3, vcc
	v_add_co_u32_e32 v8, vcc, s59, v2
	s_nop 1
	v_addc_co_u32_e32 v9, vcc, 0, v3, vcc
	v_add_co_u32_e32 v10, vcc, s60, v2
	s_nop 1
	v_addc_co_u32_e32 v11, vcc, 0, v3, vcc
	v_add_co_u32_e32 v12, vcc, s61, v2
	s_nop 1
	v_addc_co_u32_e32 v13, vcc, 0, v3, vcc
	v_add_co_u32_e32 v24, vcc, s62, v2
	s_nop 1
	v_addc_co_u32_e32 v25, vcc, 0, v3, vcc
	v_add_co_u32_e32 v50, vcc, s63, v2
	s_nop 1
	v_addc_co_u32_e32 v51, vcc, 0, v3, vcc
	v_add_co_u32_e32 v52, vcc, s64, v2
	s_nop 1
	v_addc_co_u32_e32 v53, vcc, 0, v3, vcc
	global_load_dword v59, v[4:5], off
	global_load_dword v60, v[6:7], off
	global_load_dword v61, v[8:9], off
	global_load_dword v62, v[10:11], off
	global_load_dword v63, v[12:13], off
	global_load_dword v64, v[24:25], off
	global_load_dword v65, v[50:51], off
	global_load_dword v66, v[52:53], off
	v_add_co_u32_e32 v4, vcc, s65, v2
	s_nop 1
	v_addc_co_u32_e32 v5, vcc, 0, v3, vcc
	v_add_co_u32_e32 v6, vcc, s66, v2
	s_nop 1
	v_addc_co_u32_e32 v7, vcc, 0, v3, vcc
	v_add_co_u32_e32 v8, vcc, s67, v2
	s_nop 1
	v_addc_co_u32_e32 v9, vcc, 0, v3, vcc
	v_add_co_u32_e32 v10, vcc, s68, v2
	s_nop 1
	v_addc_co_u32_e32 v11, vcc, 0, v3, vcc
	v_add_co_u32_e32 v12, vcc, s69, v2
	s_nop 1
	v_addc_co_u32_e32 v13, vcc, 0, v3, vcc
	v_add_co_u32_e32 v24, vcc, s70, v2
	s_nop 1
	v_addc_co_u32_e32 v25, vcc, 0, v3, vcc
	v_add_co_u32_e32 v50, vcc, s71, v2
	s_nop 1
	v_addc_co_u32_e32 v51, vcc, 0, v3, vcc
	v_add_co_u32_e32 v52, vcc, s72, v2
	s_nop 1
	v_addc_co_u32_e32 v53, vcc, 0, v3, vcc
	global_load_dword v67, v[4:5], off
	global_load_dword v68, v[6:7], off
	global_load_dword v69, v[8:9], off
	global_load_dword v70, v[10:11], off
	global_load_dword v71, v[12:13], off
	global_load_dword v72, v[24:25], off
	global_load_dword v73, v[50:51], off
	s_nop 0
	global_load_dword v52, v[52:53], off
	v_add_co_u32_e32 v4, vcc, s73, v2
	s_nop 1
	v_addc_co_u32_e32 v5, vcc, 0, v3, vcc
	v_add_co_u32_e32 v6, vcc, s74, v2
	s_nop 1
	v_addc_co_u32_e32 v7, vcc, 0, v3, vcc
	v_add_co_u32_e32 v8, vcc, s75, v2
	s_nop 1
	v_addc_co_u32_e32 v9, vcc, 0, v3, vcc
	v_add_co_u32_e32 v10, vcc, s76, v2
	s_nop 1
	v_addc_co_u32_e32 v11, vcc, 0, v3, vcc
	v_add_co_u32_e32 v12, vcc, s77, v2
	s_nop 1
	v_addc_co_u32_e32 v13, vcc, 0, v3, vcc
	v_add_co_u32_e32 v24, vcc, s78, v2
	s_nop 1
	v_addc_co_u32_e32 v25, vcc, 0, v3, vcc
	v_add_co_u32_e32 v50, vcc, s79, v2
	s_nop 1
	v_addc_co_u32_e32 v51, vcc, 0, v3, vcc
	v_add_co_u32_e32 v2, vcc, s80, v2
	s_nop 1
	v_addc_co_u32_e32 v3, vcc, 0, v3, vcc
	global_load_dword v4, v[4:5], off
	s_nop 0
	global_load_dword v5, v[6:7], off
	s_nop 0
	global_load_dword v6, v[8:9], off
	global_load_dword v7, v[10:11], off
	s_nop 0
	global_load_dword v8, v[12:13], off
	global_load_dword v9, v[24:25], off
	global_load_dword v10, v[50:51], off
	s_nop 0
	global_load_dword v2, v[2:3], off
	s_waitcnt vmcnt(31)
	ds_write_b32 v19, v16
	s_waitcnt vmcnt(30)
	ds_write_b32 v19, v23 offset:2064
	s_waitcnt vmcnt(29)
	ds_write_b32 v19, v49 offset:4128
	s_waitcnt vmcnt(28)
	ds_write_b32 v19, v54 offset:6192
	s_waitcnt vmcnt(27)
	ds_write_b32 v19, v55 offset:8256
	s_waitcnt vmcnt(26)
	ds_write_b32 v19, v56 offset:10320
	s_waitcnt vmcnt(25)
	ds_write_b32 v19, v57 offset:12384
	s_waitcnt vmcnt(24)
	ds_write_b32 v19, v58 offset:14448
	s_waitcnt vmcnt(23)
	ds_write_b32 v19, v59 offset:16512
	s_waitcnt vmcnt(22)
	ds_write_b32 v19, v60 offset:18576
	s_waitcnt vmcnt(21)
	ds_write_b32 v19, v61 offset:20640
	s_waitcnt vmcnt(20)
	ds_write_b32 v19, v62 offset:22704
	s_waitcnt vmcnt(19)
	ds_write_b32 v19, v63 offset:24768
	s_waitcnt vmcnt(18)
	ds_write_b32 v19, v64 offset:26832
	s_waitcnt vmcnt(17)
	ds_write_b32 v19, v65 offset:28896
	s_waitcnt vmcnt(16)
	ds_write_b32 v19, v66 offset:30960
	s_waitcnt vmcnt(15)
	ds_write_b32 v19, v67 offset:33024
	s_waitcnt vmcnt(14)
	ds_write_b32 v19, v68 offset:35088
	s_waitcnt vmcnt(13)
	ds_write_b32 v19, v69 offset:37152
	s_waitcnt vmcnt(12)
	ds_write_b32 v19, v70 offset:39216
	s_waitcnt vmcnt(11)
	ds_write_b32 v19, v71 offset:41280
	s_waitcnt vmcnt(10)
	ds_write_b32 v19, v72 offset:43344
	s_waitcnt vmcnt(9)
	ds_write_b32 v19, v73 offset:45408
	s_waitcnt vmcnt(8)
	ds_write_b32 v19, v52 offset:47472
	s_waitcnt vmcnt(7)
	ds_write_b32 v19, v4 offset:49536
	s_waitcnt vmcnt(6)
	ds_write_b32 v19, v5 offset:51600
	s_waitcnt vmcnt(5)
	ds_write_b32 v19, v6 offset:53664
	s_waitcnt vmcnt(4)
	ds_write_b32 v19, v7 offset:55728
	s_waitcnt vmcnt(3)
	ds_write_b32 v19, v8 offset:57792
	s_waitcnt vmcnt(2)
	ds_write_b32 v19, v9 offset:59856
	s_waitcnt vmcnt(1)
	ds_write_b32 v19, v10 offset:61920
	s_waitcnt vmcnt(0)
	ds_write_b32 v19, v2 offset:63984
	v_add_u32_e32 v2, s46, v26
	v_ashrrev_i32_e32 v3, 31, v2
	v_lshlrev_b64 v[2:3], 14, v[2:3]
	v_lshl_add_u64 v[2:3], s[42:43], 0, v[2:3]
	v_lshl_add_u64 v[2:3], v[2:3], 0, s[22:23]
	v_mov_b32_e32 v23, v17
	s_waitcnt lgkmcnt(0)
	s_barrier
	v_lshl_add_u64 v[6:7], v[2:3], 0, v[22:23]
	ds_read2_b32 v[2:3], v27 offset1:129
	ds_read2_b32 v[4:5], v32 offset0:2 offset1:131
	ds_read2_b32 v[8:9], v33 offset0:4 offset1:133
	ds_read2_b32 v[10:11], v34 offset0:6 offset1:135
	s_waitcnt lgkmcnt(3)
	v_cvt_pk_bf16_f32 v2, v2, v3
	s_waitcnt lgkmcnt(2)
	v_cvt_pk_bf16_f32 v3, v4, v5
	s_waitcnt lgkmcnt(1)
	v_cvt_pk_bf16_f32 v4, v8, v9
	s_waitcnt lgkmcnt(0)
	v_cvt_pk_bf16_f32 v5, v10, v11
	ds_read2_b32 v[8:9], v35 offset0:8 offset1:137
	ds_read2_b32 v[10:11], v36 offset0:10 offset1:139
	ds_read2_b32 v[24:25], v37 offset0:12 offset1:141
	ds_read2_b32 v[50:51], v38 offset0:14 offset1:143
	s_mov_b32 s22, 0x3b00000
	v_lshl_add_u64 v[12:13], v[6:7], 0, s[34:35]
	v_add_co_u32_e32 v6, vcc, s22, v6
	s_mov_b64 s[46:47], 0
	s_nop 0
	v_addc_co_u32_e32 v7, vcc, 0, v7, vcc
	global_store_dwordx4 v[6:7], v[2:5], off
	s_waitcnt lgkmcnt(3)
	s_nop 0
	v_cvt_pk_bf16_f32 v2, v8, v9
	s_waitcnt lgkmcnt(2)
	v_cvt_pk_bf16_f32 v3, v10, v11
	s_waitcnt lgkmcnt(1)
	v_cvt_pk_bf16_f32 v4, v24, v25
	s_waitcnt lgkmcnt(0)
	v_cvt_pk_bf16_f32 v5, v50, v51
	ds_read2_b32 v[6:7], v39 offset0:16 offset1:145
	ds_read2_b32 v[8:9], v40 offset0:18 offset1:147
	ds_read2_b32 v[10:11], v41 offset0:20 offset1:149
	ds_read2_b32 v[24:25], v42 offset0:22 offset1:151
	global_store_dwordx4 v[12:13], v[2:5], off offset:16
	s_waitcnt lgkmcnt(3)
	s_nop 0
	v_cvt_pk_bf16_f32 v2, v6, v7
	s_waitcnt lgkmcnt(2)
	v_cvt_pk_bf16_f32 v3, v8, v9
	s_waitcnt lgkmcnt(1)
	v_cvt_pk_bf16_f32 v4, v10, v11
	s_waitcnt lgkmcnt(0)
	v_cvt_pk_bf16_f32 v5, v24, v25
	ds_read2_b32 v[6:7], v43 offset0:24 offset1:153
	ds_read2_b32 v[8:9], v44 offset0:26 offset1:155
	ds_read2_b32 v[10:11], v45 offset0:28 offset1:157
	ds_read2_b32 v[24:25], v46 offset0:30 offset1:159
	global_store_dwordx4 v[12:13], v[2:5], off offset:32
	s_waitcnt lgkmcnt(3)
	s_nop 0
	v_cvt_pk_bf16_f32 v2, v6, v7
	s_waitcnt lgkmcnt(2)
	v_cvt_pk_bf16_f32 v3, v8, v9
	s_waitcnt lgkmcnt(1)
	v_cvt_pk_bf16_f32 v4, v10, v11
	s_waitcnt lgkmcnt(0)
	v_cvt_pk_bf16_f32 v5, v24, v25
	global_store_dwordx4 v[12:13], v[2:5], off offset:48
	s_barrier

.LBB0_578:
	v_readlane_b32 s98, v254, 12
	v_readlane_b32 s38, v254, 58
	s_barrier
	s_cmp_eq_u32 s12, 6
	s_cbranch_scc1 .Ldf_cfg6
	s_branch .Ldf_done
	s_cmpk_lt_u32 s84, 0xa6
	s_cbranch_scc1 .Ldf_done
	s_sub_u32 s66, s84, 0xa6
	s_mov_b32 s90, 0
	s_mov_b32 s91, 0x1300000
	s_mov_b32 s92, 0x3b00000
	s_movk_i32 s93, 0x5a
	s_movk_i32 s94, 0x400
	s_mov_b32 s86, 0
	s_mov_b32 s87, 0
	s_branch .Ldf_go
.Ldf_cfg6:
	s_cmp_lt_u32 s84, 16
	s_cbranch_scc1 .Ldf_done
	s_sub_u32 s66, s84, 16
	s_movk_i32 s90, 0x100
	s_mov_b32 s91, 0x6e00000
	s_mov_b32 s92, 0x9600000
	s_movk_i32 s93, 0xf0
	s_movk_i32 s94, 0x500
	s_mov_b32 s86, 0x1000000
	s_mov_b32 s87, 0x4000000
.Ldf_go:
	v_readlane_b32 s54, v254, 12
	v_readlane_b32 s55, v254, 13
	v_and_b32_e32 v34, 31, v154
	v_lshrrev_b32_e32 v35, 5, v154
	v_lshlrev_b32_e32 v38, 4, v34
	s_sub_u32 s54, s54, 0xc0
	s_subb_u32 s55, s55, 0
	s_load_dwordx4 s[56:59], s[54:55], 0x80
	s_load_dwordx2 s[62:63], s[54:55], 0x90
	s_load_dwordx2 s[64:65], s[54:55], 0xa8
	s_movk_i32 s67, 0x210
	v_mad_u32_u24 v37, v35, s67, v38
	v_lshrrev_b32_e32 v40, 2, v154
	v_and_b32_e32 v41, 3, v154
	s_movk_i32 s67, 0x4200
	v_lshlrev_b32_e32 v39, 2, v40
	v_mad_u32_u24 v39, v41, s67, v39
	v_lshlrev_b32_e32 v42, 6, v41
	s_waitcnt lgkmcnt(0)
	s_add_u32 s56, s56, s86
	s_addc_u32 s57, s57, 0
	s_add_u32 s62, s62, s87
	s_addc_u32 s63, s63, 0
	s_cmp_lt_u32 s66, s90
	s_cbranch_scc0 .Ldf_a_ff2
	s_mov_b32 s74, s66
	s_mov_b64 s[68:69], s[56:57]
	s_mov_b32 s75, s91
	s_movk_i32 s72, 0x2000
	s_movk_i32 s73, 0x1000
	s_mov_b32 s76, 4
	s_branch .Ldf_a_dec
.Ldf_a_ff2:
	s_sub_u32 s74, s66, s90
	s_mov_b64 s[68:69], s[62:63]
	s_mov_b32 s75, s92
	s_movk_i32 s72, 0x2000
	s_movk_i32 s73, 0x4000
	s_mov_b32 s76, 6
.Ldf_a_dec:
	s_lshr_b32 s77, s74, s76
	s_lshl_b32 s86, s77, s76
	s_sub_u32 s74, s74, s86
	s_lshl_b32 s86, s74, 7
	s_mul_i32 s86, s86, s72
	s_lshl_b32 s87, s77, 9
	s_add_u32 s86, s86, s87
	s_add_u32 s68, s68, s86
	s_addc_u32 s69, s69, 0
	s_lshl_b32 s86, s77, 7
	s_mul_i32 s86, s86, s73
	s_lshl_b32 s87, s74, 8
	s_add_u32 s86, s86, s87
	s_add_u32 s86, s86, s75
	s_add_u32 s70, s64, s86
	s_addc_u32 s71, s65, 0
	v_mad_u32_u24 v36, v35, s72, v38
	s_lshl_b32 s86, s72, 4
	global_load_dwordx4 v[2:5], v36, s[68:69]
	s_add_u32 s68, s68, s86
	s_addc_u32 s69, s69, 0
	global_load_dwordx4 v[6:9], v36, s[68:69]
	s_add_u32 s68, s68, s86
	s_addc_u32 s69, s69, 0
	global_load_dwordx4 v[10:13], v36, s[68:69]
	s_add_u32 s68, s68, s86
	s_addc_u32 s69, s69, 0
	global_load_dwordx4 v[14:17], v36, s[68:69]
	s_add_u32 s68, s68, s86
	s_addc_u32 s69, s69, 0
	global_load_dwordx4 v[18:21], v36, s[68:69]
	s_add_u32 s68, s68, s86
	s_addc_u32 s69, s69, 0
	global_load_dwordx4 v[22:25], v36, s[68:69]
	s_add_u32 s68, s68, s86
	s_addc_u32 s69, s69, 0
	global_load_dwordx4 v[26:29], v36, s[68:69]
	s_add_u32 s68, s68, s86
	s_addc_u32 s69, s69, 0
	global_load_dwordx4 v[30:33], v36, s[68:69]
.Ldf_loop:
	s_waitcnt vmcnt(0)
	ds_write_b128 v37, v[2:5]
	ds_write_b128 v37, v[6:9] offset:8448
	ds_write_b128 v37, v[10:13] offset:16896
	ds_write_b128 v37, v[14:17] offset:25344
	ds_write_b128 v37, v[18:21] offset:33792
	ds_write_b128 v37, v[22:25] offset:42240
	ds_write_b128 v37, v[26:29] offset:50688
	ds_write_b128 v37, v[30:33] offset:59136
	v_mad_u32_u24 v52, v40, s73, v42
	s_mov_b64 s[88:89], s[70:71]
	s_waitcnt lgkmcnt(0)
	s_barrier
	s_add_i32 s66, s66, s93
	s_cmp_lt_u32 s66, s94
	s_cbranch_scc0 .Ldf_nonext
	s_cmp_lt_u32 s66, s90
	s_cbranch_scc0 .Ldf_b_ff2
	s_mov_b32 s74, s66
	s_mov_b64 s[68:69], s[56:57]
	s_mov_b32 s75, s91
	s_movk_i32 s72, 0x2000
	s_movk_i32 s73, 0x1000
	s_mov_b32 s76, 4
	s_branch .Ldf_b_dec

.Ldf_nonext:
	ds_read_b32 v44, v39 offset:0
	ds_read_b32 v45, v39 offset:528
	ds_read_b32 v46, v39 offset:1056
	ds_read_b32 v47, v39 offset:1584
	ds_read_b32 v48, v39 offset:2112
	ds_read_b32 v49, v39 offset:2640
	ds_read_b32 v50, v39 offset:3168
	ds_read_b32 v51, v39 offset:3696
	s_waitcnt lgkmcnt(0)
	v_cvt_pk_bf16_f32 v54, v44, v45
	v_cvt_pk_bf16_f32 v55, v46, v47
	v_cvt_pk_bf16_f32 v56, v48, v49
	v_cvt_pk_bf16_f32 v57, v50, v51
	global_store_dwordx4 v52, v[54:57], s[88:89]
	s_nop 1
	ds_read_b32 v44, v39 offset:4224
	ds_read_b32 v45, v39 offset:4752
	ds_read_b32 v46, v39 offset:5280
	ds_read_b32 v47, v39 offset:5808
	ds_read_b32 v48, v39 offset:6336
	ds_read_b32 v49, v39 offset:6864
	ds_read_b32 v50, v39 offset:7392
	ds_read_b32 v51, v39 offset:7920
	s_waitcnt lgkmcnt(0)
	v_cvt_pk_bf16_f32 v54, v44, v45
	v_cvt_pk_bf16_f32 v55, v46, v47
	v_cvt_pk_bf16_f32 v56, v48, v49
	v_cvt_pk_bf16_f32 v57, v50, v51
	global_store_dwordx4 v52, v[54:57], s[88:89] offset:16
	s_nop 1
	ds_read_b32 v44, v39 offset:8448
	ds_read_b32 v45, v39 offset:8976
	ds_read_b32 v46, v39 offset:9504
	ds_read_b32 v47, v39 offset:10032
	ds_read_b32 v48, v39 offset:10560
	ds_read_b32 v49, v39 offset:11088
	ds_read_b32 v50, v39 offset:11616
	ds_read_b32 v51, v39 offset:12144
	s_waitcnt lgkmcnt(0)
	v_cvt_pk_bf16_f32 v54, v44, v45
	v_cvt_pk_bf16_f32 v55, v46, v47
	v_cvt_pk_bf16_f32 v56, v48, v49
	v_cvt_pk_bf16_f32 v57, v50, v51
	global_store_dwordx4 v52, v[54:57], s[88:89] offset:32
	s_nop 1
	ds_read_b32 v44, v39 offset:12672
	ds_read_b32 v45, v39 offset:13200
	ds_read_b32 v46, v39 offset:13728
	ds_read_b32 v47, v39 offset:14256
	ds_read_b32 v48, v39 offset:14784
	ds_read_b32 v49, v39 offset:15312
	ds_read_b32 v50, v39 offset:15840
	ds_read_b32 v51, v39 offset:16368
	s_waitcnt lgkmcnt(0)
	v_cvt_pk_bf16_f32 v54, v44, v45
	v_cvt_pk_bf16_f32 v55, v46, v47
	v_cvt_pk_bf16_f32 v56, v48, v49
	v_cvt_pk_bf16_f32 v57, v50, v51
	global_store_dwordx4 v52, v[54:57], s[88:89] offset:48
	s_nop 1
	s_barrier
	s_cmp_lt_u32 s66, s94
	s_cbranch_scc1 .Ldf_loop
	s_waitcnt vmcnt(0) lgkmcnt(0)
.Ldf_done:
	v_readlane_b32 s99, v254, 13
	v_readlane_b32 s78, v254, 14
	v_readlane_b32 s94, v254, 15
	s_movk_i32 s97, 0x7fff
	v_readlane_b32 s39, v254, 59
